# latent attention tile loop: waves 4-7 run the rotated body (P*V of the previous tile first), 4-slot K/V ring, on top of the static mix assignment
# baseline (speedup 1.0000x reference)
.LBB0_114:
	v_sub_f32_e32 v92, v92, v163
	v_sub_f32_e32 v93, v93, v163
	v_exp_f32_e32 v92, v92
	v_exp_f32_e32 v93, v93
	v_sub_f32_e32 v88, v88, v163
	v_sub_f32_e32 v94, v94, v163
	v_exp_f32_e32 v105, v88
	v_sub_f32_e32 v88, v89, v163
	v_exp_f32_e32 v94, v94
	v_sub_f32_e32 v95, v95, v163
	v_exp_f32_e32 v106, v88
	v_sub_f32_e32 v88, v90, v163
	v_exp_f32_e32 v95, v95
	v_exp_f32_e32 v107, v88
	v_sub_f32_e32 v88, v91, v163
	v_exp_f32_e32 v108, v88
	v_cvt_pk_bf16_f32 v88, v92, v93
	v_add_f32_e32 v92, 0, v92
	v_add_f32_e32 v92, v93, v92
	v_add_f32_e32 v92, v94, v92
	v_sub_f32_e32 v72, v100, v163
	v_add_f32_e32 v92, v95, v92
	v_exp_f32_e32 v100, v72
	v_sub_f32_e32 v72, v101, v163
	v_add_f32_e32 v92, v105, v92
	v_exp_f32_e32 v101, v72
	v_sub_f32_e32 v72, v102, v163
	v_add_f32_e32 v92, v106, v92
	v_exp_f32_e32 v102, v72
	v_sub_f32_e32 v72, v103, v163
	v_add_f32_e32 v92, v107, v92
	v_exp_f32_e32 v103, v72
	v_sub_f32_e32 v72, v96, v163
	v_add_f32_e32 v92, v108, v92
	v_exp_f32_e32 v96, v72
	v_sub_f32_e32 v72, v97, v163
	v_add_f32_e32 v92, v100, v92
	v_exp_f32_e32 v97, v72
	v_sub_f32_e32 v72, v98, v163
	v_add_f32_e32 v92, v101, v92
	v_exp_f32_e32 v98, v72
	v_sub_f32_e32 v72, v99, v163
	v_add_f32_e32 v92, v102, v92
	s_waitcnt lgkmcnt(0)
	v_add_f32_e32 v3, v3, v104
	v_add_f32_e32 v0, v0, v2
	v_exp_f32_e32 v99, v72
	v_add_f32_e32 v92, v103, v92
	v_mul_f32_e32 v3, 0x3fb8aa3b, v3
	v_mul_f32_e32 v0, 0x3fb8aa3b, v0
	v_add_f32_e32 v92, v96, v92
	v_exp_f32_e32 v3, v3
	v_exp_f32_e32 v0, v0
	v_add_f32_e32 v92, v97, v92
	v_add_f32_e32 v2, v98, v92
	v_add_f32_e32 v2, v99, v2
	v_cvt_pk_bf16_f32 v91, v107, v108
	v_add_f32_e32 v108, v141, v2
	v_sub_f32_e32 v2, v3, v0
	v_sub_f32_e32 v0, v84, v161
	v_exp_f32_e32 v0, v0
	v_sub_f32_e32 v3, v85, v161
	v_exp_f32_e32 v3, v3
	v_sub_f32_e32 v84, v86, v161
	v_exp_f32_e32 v84, v84
	v_sub_f32_e32 v85, v87, v161
	v_exp_f32_e32 v85, v85
	v_sub_f32_e32 v80, v80, v161
	v_add_f32_e32 v86, 0, v0
	v_exp_f32_e32 v80, v80
	v_sub_f32_e32 v81, v81, v161
	v_add_f32_e32 v86, v3, v86
	v_exp_f32_e32 v81, v81
	v_sub_f32_e32 v82, v82, v161
	v_add_f32_e32 v86, v84, v86
	v_exp_f32_e32 v82, v82
	v_sub_f32_e32 v83, v83, v161
	v_add_f32_e32 v86, v85, v86
	v_exp_f32_e32 v83, v83
	v_sub_f32_e32 v76, v76, v161
	v_add_f32_e32 v86, v80, v86
	v_exp_f32_e32 v76, v76
	v_sub_f32_e32 v77, v77, v161
	v_add_f32_e32 v86, v81, v86
	v_exp_f32_e32 v77, v77
	v_sub_f32_e32 v78, v78, v161
	v_add_f32_e32 v86, v82, v86
	v_exp_f32_e32 v78, v78
	v_sub_f32_e32 v79, v79, v161
	v_add_f32_e32 v86, v83, v86
	v_exp_f32_e32 v79, v79
	v_sub_f32_e32 v68, v68, v161
	v_add_f32_e32 v86, v76, v86
	v_exp_f32_e32 v87, v68
	v_sub_f32_e32 v68, v69, v161
	v_add_f32_e32 v86, v77, v86
	v_exp_f32_e32 v92, v68
	v_sub_f32_e32 v68, v70, v161
	v_add_f32_e32 v86, v78, v86
	v_exp_f32_e32 v93, v68
	v_sub_f32_e32 v68, v71, v161
	v_cvt_pk_bf16_f32 v89, v94, v95
	v_add_f32_e32 v86, v79, v86
	v_exp_f32_e32 v94, v68
	v_add_f32_e32 v68, v87, v86
	v_add_f32_e32 v68, v92, v68
	v_add_f32_e32 v68, v93, v68
	v_add_f32_e32 v68, v94, v68
	v_add_f32_e32 v109, v140, v68
	v_cvt_pk_bf16_f32 v68, v0, v3
	v_cvt_pk_bf16_f32 v70, v80, v81
	v_add_u32_e32 v0, 0x18000, v117
	ds_read_b64 v[80:81], v0 offset:0
	v_cvt_pk_bf16_f32 v71, v82, v83
	v_add_u32_e32 v3, 0x18000, v137
	ds_read_b64 v[82:83], v3 offset:0
	v_cvt_pk_bf16_f32 v69, v84, v85
	v_add_u32_e32 v110, 0x18000, v138
	ds_read_b64 v[84:85], v110 offset:0
	v_cvt_pk_bf16_f32 v76, v76, v77
	v_cvt_pk_bf16_f32 v77, v78, v79
	v_cvt_pk_bf16_f32 v78, v87, v92
	v_add_u32_e32 v111, 0x18000, v139
	ds_read_b64 v[86:87], v111 offset:0
	v_cvt_pk_bf16_f32 v79, v93, v94
	ds_read_b64 v[92:93], v0 offset:2048
	ds_read_b64 v[94:95], v3 offset:2048
	v_cvt_pk_bf16_f32 v74, v96, v97
	ds_read_b64 v[96:97], v110 offset:2048
	v_cvt_pk_bf16_f32 v75, v98, v99
	ds_read_b64 v[98:99], v111 offset:2048
	v_cvt_pk_bf16_f32 v72, v100, v101
	ds_read_b64 v[100:101], v0 offset:4096
	v_cvt_pk_bf16_f32 v73, v102, v103
	ds_read_b64 v[102:103], v3 offset:4096
	v_cvt_pk_bf16_f32 v90, v105, v106
	ds_read_b64 v[104:105], v110 offset:4096
	ds_read_b64 v[106:107], v111 offset:4096
	s_waitcnt lgkmcnt(8)
	s_nop 1
	v_mfma_f32_16x16x32_bf16 v[64:67], v[80:83], v[88:91], v[64:67]
	v_mfma_f32_16x16x32_bf16 v[80:83], v[80:83], v[68:71], v[60:63]
	v_mfma_f32_16x16x32_bf16 v[60:63], v[84:87], v[72:75], v[64:67]
	v_mfma_f32_16x16x32_bf16 v[64:67], v[84:87], v[76:79], v[80:83]
	ds_read_b64 v[80:81], v0 offset:6144
	ds_read_b64 v[82:83], v3 offset:6144
	ds_read_b64 v[84:85], v110 offset:6144
	ds_read_b64 v[86:87], v111 offset:6144
	s_waitcnt lgkmcnt(8)
	v_mfma_f32_16x16x32_bf16 v[56:59], v[92:95], v[88:91], v[56:59]
	v_mfma_f32_16x16x32_bf16 v[92:95], v[92:95], v[68:71], v[52:55]
	v_mfma_f32_16x16x32_bf16 v[52:55], v[96:99], v[72:75], v[56:59]
	v_mfma_f32_16x16x32_bf16 v[56:59], v[96:99], v[76:79], v[92:95]
	ds_read_b64 v[92:93], v0 offset:8192
	ds_read_b64 v[94:95], v3 offset:8192
	ds_read_b64 v[96:97], v110 offset:8192
	ds_read_b64 v[98:99], v111 offset:8192
	s_waitcnt lgkmcnt(8)
	v_mfma_f32_16x16x32_bf16 v[48:51], v[100:103], v[88:91], v[48:51]
	v_mfma_f32_16x16x32_bf16 v[100:103], v[100:103], v[68:71], v[44:47]
	v_mfma_f32_16x16x32_bf16 v[44:47], v[104:107], v[72:75], v[48:51]
	v_mfma_f32_16x16x32_bf16 v[48:51], v[104:107], v[76:79], v[100:103]
	ds_read_b64 v[100:101], v0 offset:10240
	ds_read_b64 v[102:103], v3 offset:10240
	ds_read_b64 v[104:105], v110 offset:10240
	ds_read_b64 v[106:107], v111 offset:10240
	s_waitcnt lgkmcnt(8)
	v_mfma_f32_16x16x32_bf16 v[40:43], v[80:83], v[88:91], v[40:43]
	v_mfma_f32_16x16x32_bf16 v[80:83], v[80:83], v[68:71], v[36:39]
	v_mfma_f32_16x16x32_bf16 v[36:39], v[84:87], v[72:75], v[40:43]
	v_mfma_f32_16x16x32_bf16 v[40:43], v[84:87], v[76:79], v[80:83]
	ds_read_b64 v[80:81], v0 offset:12288
	ds_read_b64 v[82:83], v3 offset:12288
	ds_read_b64 v[84:85], v110 offset:12288
	ds_read_b64 v[86:87], v111 offset:12288
	s_waitcnt lgkmcnt(8)
	v_mfma_f32_16x16x32_bf16 v[32:35], v[92:95], v[88:91], v[32:35]
	v_mfma_f32_16x16x32_bf16 v[92:95], v[92:95], v[68:71], v[28:31]
	v_mfma_f32_16x16x32_bf16 v[28:31], v[96:99], v[72:75], v[32:35]
	v_mfma_f32_16x16x32_bf16 v[32:35], v[96:99], v[76:79], v[92:95]
	ds_read_b64 v[92:93], v0 offset:14336
	ds_read_b64 v[94:95], v3 offset:14336
	ds_read_b64 v[96:97], v110 offset:14336
	ds_read_b64 v[98:99], v111 offset:14336
	s_waitcnt lgkmcnt(8)
	v_mfma_f32_16x16x32_bf16 v[24:27], v[100:103], v[88:91], v[24:27]
	v_mfma_f32_16x16x32_bf16 v[100:103], v[100:103], v[68:71], v[16:19]
	v_mfma_f32_16x16x32_bf16 v[16:19], v[104:107], v[72:75], v[24:27]
	v_mfma_f32_16x16x32_bf16 v[100:103], v[104:107], v[76:79], v[100:103]
	s_waitcnt lgkmcnt(4)
	v_mfma_f32_16x16x32_bf16 v[20:23], v[80:83], v[88:91], v[20:23]
	v_mfma_f32_16x16x32_bf16 v[24:27], v[80:83], v[68:71], v[8:11]
	v_mfma_f32_16x16x32_bf16 v[8:11], v[84:87], v[72:75], v[20:23]
	v_mfma_f32_16x16x32_bf16 v[80:83], v[84:87], v[76:79], v[24:27]
	s_waitcnt lgkmcnt(0)
	v_mfma_f32_16x16x32_bf16 v[12:15], v[92:95], v[88:91], v[12:15]
	v_mfma_f32_16x16x32_bf16 v[4:7], v[92:95], v[68:71], v[4:7]
	v_mfma_f32_16x16x32_bf16 v[68:71], v[96:99], v[72:75], v[12:15]
	v_mfma_f32_16x16x32_bf16 v[72:75], v[96:99], v[76:79], v[4:7]
	ds_bpermute_b32 v0, v136, v108
	s_waitcnt lgkmcnt(0)
	v_add_f32_e32 v0, v108, v0
	ds_bpermute_b32 v3, v135, v0
	s_waitcnt lgkmcnt(0)
	v_add_f32_e32 v0, v0, v3
	ds_bpermute_b32 v3, v136, v109
	v_div_scale_f32 v4, s[6:7], v0, v0, 1.0
	v_rcp_f32_e32 v5, v4
	s_waitcnt lgkmcnt(0)
	v_add_f32_e32 v3, v109, v3
	ds_bpermute_b32 v117, v135, v3
	v_fma_f32 v6, -v4, v5, 1.0
	v_fmac_f32_e32 v5, v6, v5
	v_div_scale_f32 v6, vcc, 1.0, v0, 1.0
	v_mul_f32_e32 v7, v6, v5
	v_fma_f32 v12, -v4, v7, v6
	v_fmac_f32_e32 v7, v12, v5
	v_fma_f32 v4, -v4, v7, v6
	s_waitcnt lgkmcnt(0)
	v_pk_add_f32 v[2:3], v[116:117], v[2:3]
	v_div_fmas_f32 v4, v4, v5, v7
	v_div_fixup_f32 v0, v4, v0, 1.0
	v_div_scale_f32 v4, s[6:7], v3, v3, v2
	v_rcp_f32_e32 v5, v4
	v_readlane_b32 s6, v217, 30
	v_readlane_b32 s7, v217, 31
	v_fma_f32 v6, -v4, v5, 1.0
	v_fmac_f32_e32 v5, v6, v5
	v_div_scale_f32 v6, vcc, v2, v3, v2
	v_mul_f32_e32 v7, v6, v5
	v_fma_f32 v12, -v4, v7, v6
	v_fmac_f32_e32 v7, v12, v5
	v_fma_f32 v4, -v4, v7, v6
	v_div_fmas_f32 v4, v4, v5, v7
	v_div_fixup_f32 v2, v4, v3, v2
	v_pk_mul_f32 v[4:5], v[64:65], v[2:3] op_sel_hi:[1,0]
	v_pk_mul_f32 v[6:7], v[66:67], v[2:3] op_sel_hi:[1,0]
	v_pk_fma_f32 v[12:13], v[60:61], v[0:1], v[4:5] op_sel_hi:[1,0,1] neg_lo:[0,0,1] neg_hi:[0,0,1]
	v_pk_fma_f32 v[6:7], v[62:63], v[0:1], v[6:7] op_sel_hi:[1,0,1] neg_lo:[0,0,1] neg_hi:[0,0,1]
	v_mul_f32_e32 v3, v13, v13
	v_fmac_f32_e32 v3, v12, v12
	v_fmac_f32_e32 v3, v6, v6
	v_fmac_f32_e32 v3, v7, v7
	v_pk_mul_f32 v[4:5], v[56:57], v[2:3] op_sel_hi:[1,0]
	v_pk_mul_f32 v[14:15], v[58:59], v[2:3] op_sel_hi:[1,0]
	v_pk_fma_f32 v[22:23], v[52:53], v[0:1], v[4:5] op_sel_hi:[1,0,1] neg_lo:[0,0,1] neg_hi:[0,0,1]
	v_pk_fma_f32 v[14:15], v[54:55], v[0:1], v[14:15] op_sel_hi:[1,0,1] neg_lo:[0,0,1] neg_hi:[0,0,1]
	v_mul_f32_e32 v4, v23, v23
	v_fmac_f32_e32 v4, v22, v22
	v_fmac_f32_e32 v4, v14, v14
	v_fmac_f32_e32 v4, v15, v15
	v_add_f32_e32 v3, v3, v4
	v_pk_mul_f32 v[4:5], v[48:49], v[2:3] op_sel_hi:[1,0]
	v_pk_mul_f32 v[20:21], v[50:51], v[2:3] op_sel_hi:[1,0]
	v_pk_fma_f32 v[44:45], v[44:45], v[0:1], v[4:5] op_sel_hi:[1,0,1] neg_lo:[0,0,1] neg_hi:[0,0,1]
	v_pk_mul_f32 v[4:5], v[40:41], v[2:3] op_sel_hi:[1,0]
	v_pk_fma_f32 v[26:27], v[46:47], v[0:1], v[20:21] op_sel_hi:[1,0,1] neg_lo:[0,0,1] neg_hi:[0,0,1]
	v_pk_fma_f32 v[24:25], v[36:37], v[0:1], v[4:5] op_sel_hi:[1,0,1] neg_lo:[0,0,1] neg_hi:[0,0,1]
	v_pk_mul_f32 v[20:21], v[42:43], v[2:3] op_sel_hi:[1,0]
	v_mov_b32_e32 v36, v25
	v_mov_b32_e32 v37, v45
	v_pk_fma_f32 v[20:21], v[38:39], v[0:1], v[20:21] op_sel_hi:[1,0,1] neg_lo:[0,0,1] neg_hi:[0,0,1]
	v_mov_b32_e32 v4, v24
	v_mov_b32_e32 v5, v44
	v_pk_mul_f32 v[36:37], v[36:37], v[36:37]
	s_nop 0
	v_pk_fma_f32 v[4:5], v[4:5], v[4:5], v[36:37]
	v_mov_b32_e32 v36, v20
	v_mov_b32_e32 v37, v26
	v_pk_fma_f32 v[4:5], v[36:37], v[36:37], v[4:5]
	v_mov_b32_e32 v36, v21
	v_mov_b32_e32 v37, v27
	v_pk_fma_f32 v[4:5], v[36:37], v[36:37], v[4:5]
	v_lshlrev_b32_e32 v37, 4, v134
	v_add_f32_e32 v3, v5, v3
	v_add_f32_e32 v3, v4, v3
	v_pk_mul_f32 v[4:5], v[32:33], v[2:3] op_sel_hi:[1,0]
	v_pk_mul_f32 v[32:33], v[34:35], v[2:3] op_sel_hi:[1,0]
	v_pk_fma_f32 v[34:35], v[28:29], v[0:1], v[4:5] op_sel_hi:[1,0,1] neg_lo:[0,0,1] neg_hi:[0,0,1]
	v_pk_mul_f32 v[4:5], v[100:101], v[2:3] op_sel_hi:[1,0]
	v_pk_mul_f32 v[28:29], v[102:103], v[2:3] op_sel_hi:[1,0]
	v_pk_fma_f32 v[16:17], v[16:17], v[0:1], v[4:5] op_sel_hi:[1,0,1] neg_lo:[0,0,1] neg_hi:[0,0,1]
	v_pk_fma_f32 v[18:19], v[18:19], v[0:1], v[28:29] op_sel_hi:[1,0,1] neg_lo:[0,0,1] neg_hi:[0,0,1]
	v_mov_b32_e32 v28, v17
	v_mov_b32_e32 v29, v35
	v_pk_fma_f32 v[30:31], v[30:31], v[0:1], v[32:33] op_sel_hi:[1,0,1] neg_lo:[0,0,1] neg_hi:[0,0,1]
	v_mov_b32_e32 v4, v16
	v_mov_b32_e32 v5, v34
	v_pk_mul_f32 v[28:29], v[28:29], v[28:29]
	s_nop 0
	v_pk_fma_f32 v[4:5], v[4:5], v[4:5], v[28:29]
	v_mov_b32_e32 v28, v18
	v_mov_b32_e32 v29, v30
	v_pk_fma_f32 v[4:5], v[28:29], v[28:29], v[4:5]
	v_mov_b32_e32 v28, v19
	v_mov_b32_e32 v29, v31
	v_pk_fma_f32 v[4:5], v[28:29], v[28:29], v[4:5]
	s_nop 0
	v_add_f32_e32 v3, v5, v3
	v_add_f32_e32 v36, v4, v3
	v_pk_mul_f32 v[4:5], v[80:81], v[2:3] op_sel_hi:[1,0]
	v_pk_mul_f32 v[28:29], v[82:83], v[2:3] op_sel_hi:[1,0]
	v_pk_fma_f32 v[32:33], v[8:9], v[0:1], v[4:5] op_sel_hi:[1,0,1] neg_lo:[0,0,1] neg_hi:[0,0,1]
	v_pk_mul_f32 v[4:5], v[72:73], v[2:3] op_sel_hi:[1,0]
	v_pk_fma_f32 v[28:29], v[10:11], v[0:1], v[28:29] op_sel_hi:[1,0,1] neg_lo:[0,0,1] neg_hi:[0,0,1]
	v_pk_fma_f32 v[10:11], v[68:69], v[0:1], v[4:5] op_sel_hi:[1,0,1] neg_lo:[0,0,1] neg_hi:[0,0,1]
	v_pk_mul_f32 v[2:3], v[74:75], v[2:3] op_sel_hi:[1,0]
	v_mov_b32_e32 v4, v11
	v_mov_b32_e32 v5, v33
	v_pk_fma_f32 v[8:9], v[70:71], v[0:1], v[2:3] op_sel_hi:[1,0,1] neg_lo:[0,0,1] neg_hi:[0,0,1]
	v_mov_b32_e32 v2, v10
	v_mov_b32_e32 v3, v32
	v_pk_mul_f32 v[4:5], v[4:5], v[4:5]
	s_nop 0
	v_pk_fma_f32 v[2:3], v[2:3], v[2:3], v[4:5]
	v_mov_b32_e32 v4, v8
	v_mov_b32_e32 v5, v28
	v_pk_fma_f32 v[2:3], v[4:5], v[4:5], v[2:3]
	v_mov_b32_e32 v4, v9
	v_mov_b32_e32 v5, v29
	v_pk_fma_f32 v[2:3], v[4:5], v[4:5], v[2:3]
	s_nop 0
	v_add_f32_e32 v0, v3, v36
	v_add_f32_e32 v0, v2, v0
	ds_bpermute_b32 v2, v136, v0
	s_waitcnt lgkmcnt(0)
	v_add_f32_e32 v0, v0, v2
	ds_bpermute_b32 v2, v135, v0
	s_waitcnt lgkmcnt(0)
	v_add_f32_e32 v0, v0, v2
	v_fmamk_f32 v0, v0, 0x3c000000, v144
	v_rsq_f32_e32 v0, v0
	v_lshl_add_u64 v[2:3], v[120:121], 1, s[6:7]
	v_mul_f32_e32 v36, v119, v0
	v_lshlrev_b32_e32 v0, 1, v118
	v_lshl_add_u64 v[2:3], v[2:3], 0, v[0:1]
	v_lshlrev_b32_e32 v0, 3, v134
	v_lshl_add_u64 v[38:39], v[2:3], 0, v[0:1]
	global_load_dwordx4 v[218:221], v37, s[92:93]
	global_load_dwordx4 v[222:225], v37, s[92:93] offset:64
	global_load_dwordx4 v[226:229], v37, s[92:93] offset:128
	global_load_dwordx4 v[230:233], v37, s[92:93] offset:192
	global_load_dwordx4 v[234:237], v37, s[92:93] offset:256
	global_load_dwordx4 v[238:241], v37, s[92:93] offset:320
	global_load_dwordx4 v[242:245], v37, s[92:93] offset:384
	global_load_dwordx4 v[246:249], v37, s[92:93] offset:448
	v_pk_mul_f32 v[12:13], v[12:13], v[36:37] op_sel_hi:[1,0]
	v_pk_mul_f32 v[6:7], v[6:7], v[36:37] op_sel_hi:[1,0]
	v_pk_mul_f32 v[8:9], v[8:9], v[36:37] op_sel_hi:[1,0]
	s_waitcnt vmcnt(0)
	v_pk_mul_f32 v[4:5], v[220:221], v[6:7]
	v_pk_mul_f32 v[2:3], v[218:219], v[12:13]
	v_pk_mul_f32 v[6:7], v[22:23], v[36:37] op_sel_hi:[1,0]
	v_cvt_pk_bf16_f32 v2, v2, v3
	v_cvt_pk_bf16_f32 v3, v4, v5
	global_store_dwordx2 v[38:39], v[2:3], off
	v_pk_mul_f32 v[12:13], v[14:15], v[36:37] op_sel_hi:[1,0]
	v_pk_mul_f32 v[2:3], v[222:223], v[6:7]
	v_pk_mul_f32 v[4:5], v[224:225], v[12:13]
	v_cvt_pk_bf16_f32 v2, v2, v3
	v_cvt_pk_bf16_f32 v3, v4, v5
	global_store_dwordx2 v[38:39], v[2:3], off offset:32
	v_pk_mul_f32 v[6:7], v[44:45], v[36:37] op_sel_hi:[1,0]
	v_pk_mul_f32 v[12:13], v[26:27], v[36:37] op_sel_hi:[1,0]
	v_pk_mul_f32 v[2:3], v[226:227], v[6:7]
	v_pk_mul_f32 v[4:5], v[228:229], v[12:13]
	v_cvt_pk_bf16_f32 v2, v2, v3
	v_cvt_pk_bf16_f32 v3, v4, v5
	global_store_dwordx2 v[38:39], v[2:3], off offset:64
	v_pk_mul_f32 v[6:7], v[24:25], v[36:37] op_sel_hi:[1,0]
	v_pk_mul_f32 v[12:13], v[20:21], v[36:37] op_sel_hi:[1,0]
	v_pk_mul_f32 v[2:3], v[230:231], v[6:7]
	v_pk_mul_f32 v[4:5], v[232:233], v[12:13]
	v_cvt_pk_bf16_f32 v2, v2, v3
	v_cvt_pk_bf16_f32 v3, v4, v5
	global_store_dwordx2 v[38:39], v[2:3], off offset:96
	v_pk_mul_f32 v[6:7], v[34:35], v[36:37] op_sel_hi:[1,0]
	v_pk_mul_f32 v[12:13], v[30:31], v[36:37] op_sel_hi:[1,0]
	v_pk_mul_f32 v[2:3], v[234:235], v[6:7]
	v_pk_mul_f32 v[4:5], v[236:237], v[12:13]
	v_cvt_pk_bf16_f32 v2, v2, v3
	v_cvt_pk_bf16_f32 v3, v4, v5
	global_store_dwordx2 v[38:39], v[2:3], off offset:128
	v_pk_mul_f32 v[6:7], v[16:17], v[36:37] op_sel_hi:[1,0]
	v_pk_mul_f32 v[12:13], v[18:19], v[36:37] op_sel_hi:[1,0]
	v_pk_mul_f32 v[2:3], v[238:239], v[6:7]
	v_pk_mul_f32 v[4:5], v[240:241], v[12:13]
	v_cvt_pk_bf16_f32 v2, v2, v3
	v_cvt_pk_bf16_f32 v3, v4, v5
	global_store_dwordx2 v[38:39], v[2:3], off offset:160
	v_pk_mul_f32 v[6:7], v[32:33], v[36:37] op_sel_hi:[1,0]
	v_pk_mul_f32 v[12:13], v[28:29], v[36:37] op_sel_hi:[1,0]
	v_pk_mul_f32 v[2:3], v[242:243], v[6:7]
	v_pk_mul_f32 v[4:5], v[244:245], v[12:13]
	v_cvt_pk_bf16_f32 v2, v2, v3
	v_cvt_pk_bf16_f32 v3, v4, v5
	global_store_dwordx2 v[38:39], v[2:3], off offset:192
	v_pk_mul_f32 v[6:7], v[10:11], v[36:37] op_sel_hi:[1,0]
	v_pk_mul_f32 v[4:5], v[248:249], v[8:9]
	v_pk_mul_f32 v[2:3], v[246:247], v[6:7]
	s_nop 0
	v_cvt_pk_bf16_f32 v2, v2, v3
	v_cvt_pk_bf16_f32 v3, v4, v5
	global_store_dwordx2 v[38:39], v[2:3], off offset:224
